# SWA/MLA: prefetch the item's z-gate rows at the item prologue into spare registers (epilogue uses registers, no load)
# baseline (speedup 1.0000x reference)
; DI unsigned pack2(float a, float b) { f32x2_t v = {a, b}; bf16x2_t r = __builtin_convertvector(v, bf16x2_t); return __builtin_bit_cast(unsigned, r); }
; DI float bflo(unsigned u) { return __uint_as_float(u << 16); }
; DI float bfhi(unsigned u) { return __uint_as_float(u & 0xffff0000u); }
; DI float siluf_(float x) { return x * __builtin_amdgcn_rcpf(1.f + __expf(-x)); }
; DI void attn_write_staged(const f32x16& o0, const f32x16& o1, bf16_t* og, const bf16_t* z, size_t tok0, int head, int lane, bf16_t* wl) {
;   const int q = lane & 31, h = lane >> 5;
; #pragma unroll
;   for (int dt = 0; dt < 2; ++dt)
; #pragma unroll
;     for (int q4 = 0; q4 < 4; ++q4) {
;       const f32x16& o = dt ? o1 : o0;
;       *(uint2*)(wl + q * 72 + dt * 32 + 8 * q4 + 4 * h) = make_uint2(pack2(o[4 * q4], o[4 * q4 + 1]), pack2(o[4 * q4 + 2], o[4 * q4 + 3]));
;     }
; #pragma unroll
;   for (int k = 0; k < 4; ++k) {
;     const int ci = lane + 64 * k, row = ci >> 3, c8 = ci & 7;
;     const u32x4 ov = *(const u32x4*)(wl + row * 72 + c8 * 8);
;     const size_t off = (tok0 + row) * 1024 + head * 64 + c8 * 8;
;     const u32x4 zv = ldg16(z + off);
;     u32x4 r;
;     r.x = pack2(bflo(ov.x) * siluf_(bflo(zv.x)), bfhi(ov.x) * siluf_(bfhi(zv.x)));
;     r.y = pack2(bflo(ov.y) * siluf_(bflo(zv.y)), bfhi(ov.y) * siluf_(bfhi(zv.y)));
;     r.z = pack2(bflo(ov.z) * siluf_(bflo(zv.z)), bfhi(ov.z) * siluf_(bfhi(zv.z)));
;     r.w = pack2(bflo(ov.w) * siluf_(bflo(zv.w)), bfhi(ov.w) * siluf_(bfhi(zv.w)));
;     *(u32x4*)(og + off) = r;
;   }
; DI void phase_attn_swa(const Params& P, const float* sinks, bf16_t* og, unsigned char* smem, int L, int G) {
;     ...
;     const float il = 1.f / l;
; #pragma unroll
;     for (int q = 0; q < 16; ++q) { o0[q] *= il; o1[q] *= il; }
;     attn_write_staged(o0, o1, og, big + SW_Z, (size_t)b * SEQ + t0, head, lane, (bf16_t*)(smem + 40960) + w * (32 * 72));
.LBB0_337:
	s_mov_b32 s41, s39
	v_lshlrev_b32_e32 v35, 6, v173
	v_lshl_add_u64 v[32:33], v[148:149], 0, s[40:41]
	v_or_b32_e32 v35, v35, v130
	v_or_b32_e32 v36, v32, v132
	v_mov_b32_e32 v37, v33
	v_lshlrev_b64 v[40:41], 11, v[36:37]
	v_lshlrev_b32_e32 v35, 1, v35
	v_or_b32_e32 v40, v40, v35
	v_lshl_add_u64 v[36:37], s[36:37], 0, v[40:41]
	v_div_scale_f32 v42, s[0:1], v34, v34, 1.0
	v_rcp_f32_e32 v43, v42
	v_div_scale_f32 v44, vcc, 1.0, v34, 1.0
	v_add_u32_e32 v45, 0xa000, v166
	v_fma_f32 v46, -v42, v43, 1.0
	v_fmac_f32_e32 v43, v46, v43
	v_mul_f32_e32 v46, v44, v43
	v_fma_f32 v47, -v42, v46, v44
	v_fmac_f32_e32 v46, v47, v43
	v_fma_f32 v42, -v42, v46, v44
	v_div_fmas_f32 v42, v42, v43, v46
	v_div_fixup_f32 v34, v42, v34, 1.0
	v_pk_mul_f32 v[0:1], v[34:35], v[0:1] op_sel_hi:[0,1]
	v_pk_mul_f32 v[2:3], v[34:35], v[2:3] op_sel_hi:[0,1]
	v_pk_mul_f32 v[4:5], v[34:35], v[4:5] op_sel_hi:[0,1]
	v_pk_mul_f32 v[20:21], v[20:21], v[34:35] op_sel_hi:[1,0]
	v_pk_mul_f32 v[6:7], v[34:35], v[6:7] op_sel_hi:[0,1]
	v_pk_mul_f32 v[22:23], v[22:23], v[34:35] op_sel_hi:[1,0]
	v_pk_mul_f32 v[24:25], v[24:25], v[34:35] op_sel_hi:[1,0]
	v_pk_mul_f32 v[10:11], v[34:35], v[10:11] op_sel_hi:[0,1]
	v_pk_mul_f32 v[26:27], v[26:27], v[34:35] op_sel_hi:[1,0]
	v_pk_mul_f32 v[12:13], v[34:35], v[12:13] op_sel_hi:[0,1]
	v_pk_mul_f32 v[16:17], v[16:17], v[34:35] op_sel_hi:[1,0]
	v_pk_mul_f32 v[18:19], v[18:19], v[34:35] op_sel_hi:[1,0]
	v_pk_mul_f32 v[8:9], v[34:35], v[8:9] op_sel_hi:[0,1]
	v_pk_mul_f32 v[28:29], v[28:29], v[34:35] op_sel_hi:[1,0]
	v_pk_mul_f32 v[14:15], v[34:35], v[14:15] op_sel_hi:[0,1]
	v_pk_mul_f32 v[30:31], v[30:31], v[34:35] op_sel_hi:[1,0]
	v_cvt_pk_bf16_f32 v0, v0, v1
	v_cvt_pk_bf16_f32 v1, v2, v3
	v_cvt_pk_bf16_f32 v2, v4, v5
	v_cvt_pk_bf16_f32 v3, v6, v7
	v_cvt_pk_bf16_f32 v5, v10, v11
	v_cvt_pk_bf16_f32 v6, v12, v13
	v_cvt_pk_bf16_f32 v10, v20, v21
	v_cvt_pk_bf16_f32 v11, v22, v23
	v_cvt_pk_bf16_f32 v12, v24, v25
	v_cvt_pk_bf16_f32 v13, v26, v27
	v_cvt_pk_bf16_f32 v4, v8, v9
	v_cvt_pk_bf16_f32 v7, v14, v15
	v_cvt_pk_bf16_f32 v8, v16, v17
	v_cvt_pk_bf16_f32 v9, v18, v19
	v_cvt_pk_bf16_f32 v14, v28, v29
	v_cvt_pk_bf16_f32 v15, v30, v31
	ds_write2_b64 v45, v[0:1], v[2:3] offset1:2
	ds_write2_b64 v45, v[4:5], v[6:7] offset0:4 offset1:6
	ds_write2_b64 v45, v[8:9], v[10:11] offset0:8 offset1:10
	ds_write2_b64 v45, v[12:13], v[14:15] offset0:12 offset1:14
	ds_read_b128 v[0:3], v167 offset:40960
	ds_read_b128 v[4:7], v167 offset:42112
	s_add_i32 s45, s45, s74
	s_cmpk_gt_i32 s45, 0xfff
	s_waitcnt lgkmcnt(1)
	v_lshlrev_b32_e32 v8, 16, v0
	v_and_b32_e32 v9, 0xffff0000, v0
	v_lshlrev_b32_e32 v0, 16, v1
	v_and_b32_e32 v1, 0xffff0000, v1
	s_waitcnt vmcnt(0)
	v_mov_b32_e32 v36, v200
	v_mov_b32_e32 v37, v201
	v_mov_b32_e32 v38, v202
	v_mov_b32_e32 v39, v203
	v_lshlrev_b32_e32 v10, 16, v36
	v_and_b32_e32 v11, 0xffff0000, v36
	v_lshlrev_b32_e32 v12, 16, v37
	v_and_b32_e32 v13, 0xffff0000, v37
	v_mul_f32_e32 v16, 0xbfb8aa3b, v10
	v_mul_f32_e32 v17, 0xbfb8aa3b, v11
	v_mul_f32_e32 v18, 0xbfb8aa3b, v12
	v_mul_f32_e32 v19, 0xbfb8aa3b, v13
	v_exp_f32_e32 v16, v16
	v_exp_f32_e32 v17, v17
	v_exp_f32_e32 v18, v18
	v_exp_f32_e32 v19, v19
	v_lshlrev_b32_e32 v14, 16, v38
	v_and_b32_e32 v15, 0xffff0000, v38
	v_add_f32_e32 v16, 1.0, v16
	v_add_f32_e32 v17, 1.0, v17
	v_add_f32_e32 v18, 1.0, v18
	v_add_f32_e32 v19, 1.0, v19
	v_mul_f32_e32 v20, 0xbfb8aa3b, v14
	v_mul_f32_e32 v21, 0xbfb8aa3b, v15
	v_rcp_f32_e32 v16, v16
	v_rcp_f32_e32 v17, v17
	v_rcp_f32_e32 v18, v18
	v_rcp_f32_e32 v19, v19
	v_exp_f32_e32 v20, v20
	v_exp_f32_e32 v21, v21
	v_pk_mul_f32 v[10:11], v[16:17], v[10:11]
	v_pk_mul_f32 v[12:13], v[18:19], v[12:13]
	v_add_f32_e32 v20, 1.0, v20
	v_pk_mul_f32 v[8:9], v[10:11], v[8:9]
	v_pk_mul_f32 v[10:11], v[12:13], v[0:1]
	v_add_f32_e32 v1, 1.0, v21
	v_rcp_f32_e32 v20, v20
	v_rcp_f32_e32 v21, v1
	v_lshlrev_b32_e32 v12, 16, v39
	v_cvt_pk_bf16_f32 v0, v8, v9
	v_lshlrev_b32_e32 v8, 16, v2
	v_and_b32_e32 v9, 0xffff0000, v2
	v_and_b32_e32 v13, 0xffff0000, v39
	v_mul_f32_e32 v2, 0xbfb8aa3b, v12
	v_cvt_pk_bf16_f32 v1, v10, v11
	v_pk_mul_f32 v[10:11], v[20:21], v[14:15]
	v_exp_f32_e32 v2, v2
	v_mul_f32_e32 v14, 0xbfb8aa3b, v13
	v_exp_f32_e32 v14, v14
	v_pk_mul_f32 v[8:9], v[10:11], v[8:9]
	v_add_f32_e32 v2, 1.0, v2
	v_rcp_f32_e32 v10, v2
	v_add_f32_e32 v2, 1.0, v14
	v_rcp_f32_e32 v11, v2
	v_cvt_pk_bf16_f32 v2, v8, v9
	v_lshlrev_b32_e32 v8, 16, v3
	v_and_b32_e32 v9, 0xffff0000, v3
	v_pk_mul_f32 v[10:11], v[10:11], v[12:13]
	s_waitcnt lgkmcnt(0)
; DI unsigned pack2(float a, float b) { f32x2_t v = {a, b}; bf16x2_t r = __builtin_convertvector(v, bf16x2_t); return __builtin_bit_cast(unsigned, r); }
; DI float bflo(unsigned u) { return __uint_as_float(u << 16); }
; DI float bfhi(unsigned u) { return __uint_as_float(u & 0xffff0000u); }
; DI float siluf_(float x) { return x * __builtin_amdgcn_rcpf(1.f + __expf(-x)); }
; DI void attn_write_staged(const f32x16& o0, const f32x16& o1, bf16_t* og, const bf16_t* z, size_t tok0, int head, int lane, bf16_t* wl) {
;     ...
; #pragma unroll
;   for (int k = 0; k < 4; ++k) {
;     const int ci = lane + 64 * k, row = ci >> 3, c8 = ci & 7;
;     const u32x4 ov = *(const u32x4*)(wl + row * 72 + c8 * 8);
;     const size_t off = (tok0 + row) * 1024 + head * 64 + c8 * 8;
;     const u32x4 zv = ldg16(z + off);
;     u32x4 r;
;     r.x = pack2(bflo(ov.x) * siluf_(bflo(zv.x)), bfhi(ov.x) * siluf_(bfhi(zv.x)));
;     r.y = pack2(bflo(ov.y) * siluf_(bflo(zv.y)), bfhi(ov.y) * siluf_(bfhi(zv.y)));
;     r.z = pack2(bflo(ov.z) * siluf_(bflo(zv.z)), bfhi(ov.z) * siluf_(bfhi(zv.z)));
;     r.w = pack2(bflo(ov.w) * siluf_(bflo(zv.w)), bfhi(ov.w) * siluf_(bfhi(zv.w)));
;     *(u32x4*)(og + off) = r;
;   }
	v_lshlrev_b32_e32 v12, 16, v4
	v_pk_mul_f32 v[8:9], v[10:11], v[8:9]
	v_or_b32_e32 v10, v32, v136
	v_cvt_pk_bf16_f32 v3, v8, v9
	v_lshl_add_u64 v[8:9], s[94:95], 0, v[40:41]
	global_store_dwordx4 v[8:9], v[0:3], off
	v_mov_b32_e32 v11, v33
	v_and_b32_e32 v13, 0xffff0000, v4
	v_or_b32_e32 v0, v32, v134
	v_mov_b32_e32 v1, v33
	v_lshlrev_b64 v[8:9], 11, v[0:1]
	v_or_b32_e32 v8, v8, v35
	v_lshl_add_u64 v[0:1], s[36:37], 0, v[8:9]
	v_lshlrev_b32_e32 v4, 16, v5
	v_and_b32_e32 v5, 0xffff0000, v5
	v_lshlrev_b32_e32 v14, 16, v6
	v_and_b32_e32 v15, 0xffff0000, v6
	v_lshlrev_b32_e32 v6, 16, v7
	v_and_b32_e32 v7, 0xffff0000, v7
	v_lshlrev_b64 v[10:11], 11, v[10:11]
	v_lshl_add_u64 v[8:9], s[94:95], 0, v[8:9]
	v_or_b32_e32 v10, v10, v35
	v_or_b32_e32 v32, v32, v138
	v_mov_b32_e32 v0, v204
	v_mov_b32_e32 v1, v205
	v_mov_b32_e32 v2, v206
	v_mov_b32_e32 v3, v207
	v_lshlrev_b32_e32 v16, 16, v0
	v_and_b32_e32 v17, 0xffff0000, v0
	v_lshlrev_b32_e32 v0, 16, v1
	v_and_b32_e32 v1, 0xffff0000, v1
	v_lshlrev_b32_e32 v18, 16, v2
	v_and_b32_e32 v19, 0xffff0000, v2
	v_lshlrev_b32_e32 v2, 16, v3
	v_and_b32_e32 v3, 0xffff0000, v3
	v_mul_f32_e32 v20, 0xbfb8aa3b, v16
	v_mul_f32_e32 v21, 0xbfb8aa3b, v17
	v_mul_f32_e32 v22, 0xbfb8aa3b, v0
	v_mul_f32_e32 v23, 0xbfb8aa3b, v1
	v_mul_f32_e32 v24, 0xbfb8aa3b, v18
	v_mul_f32_e32 v25, 0xbfb8aa3b, v19
	v_mul_f32_e32 v26, 0xbfb8aa3b, v2
	v_mul_f32_e32 v27, 0xbfb8aa3b, v3
	v_exp_f32_e32 v20, v20
	v_exp_f32_e32 v21, v21
	v_exp_f32_e32 v22, v22
	v_exp_f32_e32 v23, v23
	v_exp_f32_e32 v24, v24
	v_exp_f32_e32 v25, v25
	v_exp_f32_e32 v26, v26
	v_exp_f32_e32 v27, v27
	v_add_f32_e32 v20, 1.0, v20
	v_add_f32_e32 v21, 1.0, v21
	v_add_f32_e32 v22, 1.0, v22
	v_add_f32_e32 v23, 1.0, v23
	v_add_f32_e32 v24, 1.0, v24
	v_add_f32_e32 v25, 1.0, v25
	v_add_f32_e32 v26, 1.0, v26
	v_add_f32_e32 v27, 1.0, v27
	v_rcp_f32_e32 v20, v20
	v_rcp_f32_e32 v21, v21
	v_rcp_f32_e32 v22, v22
	v_rcp_f32_e32 v23, v23
	v_rcp_f32_e32 v24, v24
	v_rcp_f32_e32 v25, v25
	v_rcp_f32_e32 v26, v26
	v_rcp_f32_e32 v27, v27
	v_pk_mul_f32 v[16:17], v[20:21], v[16:17]
	v_pk_mul_f32 v[0:1], v[22:23], v[0:1]
	v_pk_mul_f32 v[18:19], v[24:25], v[18:19]
	v_pk_mul_f32 v[2:3], v[26:27], v[2:3]
	v_pk_mul_f32 v[12:13], v[16:17], v[12:13]
	v_pk_mul_f32 v[4:5], v[0:1], v[4:5]
	v_pk_mul_f32 v[14:15], v[18:19], v[14:15]
	v_pk_mul_f32 v[6:7], v[2:3], v[6:7]
	v_cvt_pk_bf16_f32 v0, v12, v13
	v_cvt_pk_bf16_f32 v1, v4, v5
	v_cvt_pk_bf16_f32 v2, v14, v15
	v_cvt_pk_bf16_f32 v3, v6, v7
	global_store_dwordx4 v[8:9], v[0:3], off
	v_lshlrev_b64 v[12:13], 11, v[32:33]
	ds_read_b128 v[4:7], v167 offset:43264
	v_lshl_add_u64 v[0:1], s[36:37], 0, v[10:11]
	v_lshl_add_u64 v[14:15], s[94:95], 0, v[10:11]
	ds_read_b128 v[8:11], v167 offset:44416
	s_waitcnt lgkmcnt(1)
	v_lshlrev_b32_e32 v18, 16, v4
	v_and_b32_e32 v19, 0xffff0000, v4
	v_lshlrev_b32_e32 v4, 16, v5
	v_and_b32_e32 v5, 0xffff0000, v5
	v_lshlrev_b32_e32 v20, 16, v6
	v_and_b32_e32 v21, 0xffff0000, v6
	v_lshlrev_b32_e32 v6, 16, v7
	v_and_b32_e32 v7, 0xffff0000, v7
	v_or_b32_e32 v12, v12, v35
	v_lshl_add_u64 v[16:17], s[36:37], 0, v[12:13]
	v_mov_b32_e32 v0, v208
	v_mov_b32_e32 v1, v209
	v_mov_b32_e32 v2, v210
	v_mov_b32_e32 v3, v211
	v_lshlrev_b32_e32 v22, 16, v0
	v_and_b32_e32 v23, 0xffff0000, v0
	v_lshlrev_b32_e32 v0, 16, v1
	v_and_b32_e32 v1, 0xffff0000, v1
	v_lshlrev_b32_e32 v24, 16, v2
	v_and_b32_e32 v25, 0xffff0000, v2
	v_lshlrev_b32_e32 v2, 16, v3
	v_and_b32_e32 v3, 0xffff0000, v3
	v_mul_f32_e32 v26, 0xbfb8aa3b, v22
	v_mul_f32_e32 v27, 0xbfb8aa3b, v23
	v_mul_f32_e32 v28, 0xbfb8aa3b, v0
	v_mul_f32_e32 v29, 0xbfb8aa3b, v1
	v_mul_f32_e32 v30, 0xbfb8aa3b, v24
	v_mul_f32_e32 v31, 0xbfb8aa3b, v25
	v_mul_f32_e32 v32, 0xbfb8aa3b, v2
	v_mul_f32_e32 v33, 0xbfb8aa3b, v3
	v_exp_f32_e32 v26, v26
	v_exp_f32_e32 v27, v27
	v_exp_f32_e32 v28, v28
	v_exp_f32_e32 v29, v29
	v_exp_f32_e32 v30, v30
	v_exp_f32_e32 v31, v31
	v_exp_f32_e32 v32, v32
	v_exp_f32_e32 v33, v33
	v_add_f32_e32 v26, 1.0, v26
	v_add_f32_e32 v27, 1.0, v27
	v_add_f32_e32 v28, 1.0, v28
	v_add_f32_e32 v29, 1.0, v29
	v_add_f32_e32 v30, 1.0, v30
	v_add_f32_e32 v31, 1.0, v31
	v_add_f32_e32 v32, 1.0, v32
	v_add_f32_e32 v33, 1.0, v33
	v_rcp_f32_e32 v26, v26
	v_rcp_f32_e32 v27, v27
	v_rcp_f32_e32 v28, v28
	v_rcp_f32_e32 v29, v29
	v_rcp_f32_e32 v30, v30
	v_rcp_f32_e32 v31, v31
	v_rcp_f32_e32 v32, v32
	v_rcp_f32_e32 v33, v33
	v_pk_mul_f32 v[22:23], v[26:27], v[22:23]
	v_pk_mul_f32 v[0:1], v[28:29], v[0:1]
	v_pk_mul_f32 v[24:25], v[30:31], v[24:25]
	v_pk_mul_f32 v[2:3], v[32:33], v[2:3]
	v_pk_mul_f32 v[18:19], v[22:23], v[18:19]
	v_pk_mul_f32 v[4:5], v[0:1], v[4:5]
	v_pk_mul_f32 v[20:21], v[24:25], v[20:21]
	v_pk_mul_f32 v[6:7], v[2:3], v[6:7]
	v_cvt_pk_bf16_f32 v0, v18, v19
	v_cvt_pk_bf16_f32 v1, v4, v5
	v_cvt_pk_bf16_f32 v2, v20, v21
	v_cvt_pk_bf16_f32 v3, v6, v7
	global_store_dwordx4 v[14:15], v[0:3], off
	v_lshl_add_u64 v[4:5], s[94:95], 0, v[12:13]
	s_waitcnt lgkmcnt(0)
	v_lshlrev_b32_e32 v6, 16, v8
	v_and_b32_e32 v7, 0xffff0000, v8
	v_lshlrev_b32_e32 v8, 16, v9
	v_and_b32_e32 v9, 0xffff0000, v9
	v_lshlrev_b32_e32 v12, 16, v10
	v_and_b32_e32 v13, 0xffff0000, v10
	v_lshlrev_b32_e32 v10, 16, v11
	v_and_b32_e32 v11, 0xffff0000, v11
	v_mov_b32_e32 v0, v212
	v_mov_b32_e32 v1, v213
	v_mov_b32_e32 v2, v214
	v_mov_b32_e32 v3, v215
	v_lshlrev_b32_e32 v14, 16, v0
	v_and_b32_e32 v15, 0xffff0000, v0
	v_lshlrev_b32_e32 v0, 16, v1
	v_and_b32_e32 v1, 0xffff0000, v1
	v_lshlrev_b32_e32 v16, 16, v2
	v_and_b32_e32 v17, 0xffff0000, v2
	v_lshlrev_b32_e32 v2, 16, v3
	v_and_b32_e32 v3, 0xffff0000, v3
	v_mul_f32_e32 v18, 0xbfb8aa3b, v14
	v_mul_f32_e32 v19, 0xbfb8aa3b, v15
	v_mul_f32_e32 v20, 0xbfb8aa3b, v0
	v_mul_f32_e32 v21, 0xbfb8aa3b, v1
	v_mul_f32_e32 v22, 0xbfb8aa3b, v16
	v_mul_f32_e32 v23, 0xbfb8aa3b, v17
	v_mul_f32_e32 v24, 0xbfb8aa3b, v2
	v_mul_f32_e32 v25, 0xbfb8aa3b, v3
	v_exp_f32_e32 v18, v18
	v_exp_f32_e32 v19, v19
	v_exp_f32_e32 v20, v20
	v_exp_f32_e32 v21, v21
	v_exp_f32_e32 v22, v22
	v_exp_f32_e32 v23, v23
	v_exp_f32_e32 v24, v24
	v_exp_f32_e32 v25, v25
	v_add_f32_e32 v18, 1.0, v18
	v_add_f32_e32 v19, 1.0, v19
	v_add_f32_e32 v20, 1.0, v20
	v_add_f32_e32 v21, 1.0, v21
	v_add_f32_e32 v22, 1.0, v22
	v_add_f32_e32 v23, 1.0, v23
	v_add_f32_e32 v24, 1.0, v24
	v_add_f32_e32 v25, 1.0, v25
	v_rcp_f32_e32 v18, v18
	v_rcp_f32_e32 v19, v19
	v_rcp_f32_e32 v20, v20
	v_rcp_f32_e32 v21, v21
	v_rcp_f32_e32 v22, v22
	v_rcp_f32_e32 v23, v23
	v_rcp_f32_e32 v24, v24
	v_rcp_f32_e32 v25, v25
	v_pk_mul_f32 v[14:15], v[18:19], v[14:15]
	v_pk_mul_f32 v[0:1], v[20:21], v[0:1]
	v_pk_mul_f32 v[16:17], v[22:23], v[16:17]
	v_pk_mul_f32 v[2:3], v[24:25], v[2:3]
	v_pk_mul_f32 v[6:7], v[14:15], v[6:7]
	v_pk_mul_f32 v[8:9], v[0:1], v[8:9]
	v_pk_mul_f32 v[12:13], v[16:17], v[12:13]
	v_pk_mul_f32 v[10:11], v[2:3], v[10:11]
	v_cvt_pk_bf16_f32 v0, v6, v7
	v_cvt_pk_bf16_f32 v1, v8, v9
	v_cvt_pk_bf16_f32 v2, v12, v13
	v_cvt_pk_bf16_f32 v3, v10, v11
	global_store_dwordx4 v[4:5], v[0:3], off
	s_cbranch_scc1 .LBB0_352

; DI void attn_write_staged(const f32x16& o0, const f32x16& o1, bf16_t* og, const bf16_t* z, size_t tok0, int head, int lane, bf16_t* wl) {
;     ...
;   for (int k = 0; k < 4; ++k) {
;     const int ci = lane + 64 * k, row = ci >> 3, c8 = ci & 7;
;     const u32x4 ov = *(const u32x4*)(wl + row * 72 + c8 * 8);
;     const size_t off = (tok0 + row) * 1024 + head * 64 + c8 * 8;
;     const u32x4 zv = ldg16(z + off);
; DI void phase_attn_swa(const Params& P, const float* sinks, bf16_t* og, unsigned char* smem, int L, int G) {
;     ...
;     int qt, bg; gqa_item(it, L, G, gi, qt, bg);
;     const int b = bg >> 2, g = bg & 3;
;     const int t0 = qt * 32, t = t0 + r, head = g * 4 + w;
;     const size_t tok = (size_t)b * SEQ + t;
;     bf16x8 qf[4];
; #pragma unroll
;     for (int ks = 0; ks < 4; ++ks) qf[ks] = *(const bf16x8*)(big + SW_Q + tok * 1024 + head * 64 + ks * 16 + 8 * h);
;     f32x16 o0, o1, s[2]; o_zero(o0, o1);
;     float m = sinks[head] * LOG2E, l = 1.f;
;     const bf16_t* kb = big + SW_K + (size_t)b * SEQ * 256 + g * 64;
;     const bf16_t* vb = big + SW_VT + (size_t)((b * 4 + g) * 64) * SEQ;
;     const int jlo = (t0 - 127 > 0 ? t0 - 127 : 0) >> 6, jhi = (t0 + 31) >> 6;
;     KVR R; kv64_fetch(R, kb, 256, vb, SEQ, jlo * 64, true, tid);
;     __syncthreads();
;     kv64_store(R, sK, sVt, tid);
;     if (jlo < jhi) kv64_fetch(R, kb, 256, vb, SEQ, jlo * 64 + 64, true, tid);
.LBB0_342:
	v_ashrrev_i32_e32 v0, 2, v2
	s_lshl_b32 s40, s41, 5
	v_ashrrev_i32_e32 v1, 31, v0
	v_or_b32_e32 v150, s40, v135
	v_lshlrev_b64 v[148:149], 11, v[0:1]
	v_mov_b32_e32 v151, v129
	v_and_b32_e32 v3, 3, v2
	v_lshl_add_u64 v[4:5], v[148:149], 0, v[150:151]
	v_lshl_or_b32 v173, v3, 2, v133
	v_lshlrev_b64 v[4:5], 11, v[4:5]
	s_max_i32 s0, s40, 0x7f
	v_lshl_add_u64 v[4:5], s[76:77], 0, v[4:5]
	v_lshlrev_b32_e32 v128, 7, v173
	v_lshlrev_b64 v[0:1], 20, v[0:1]
	v_lshlrev_b32_e32 v2, 6, v2
	s_add_i32 s46, s0, 0xffffff81
	v_lshl_add_u64 v[4:5], v[4:5], 0, v[128:129]
	v_lshl_add_u64 v[0:1], s[30:31], 0, v[0:1]
	v_lshlrev_b32_e32 v128, 7, v3
	v_ashrrev_i32_e32 v3, 31, v2
	s_and_b32 s38, s46, 0xffffffc0
	v_lshl_add_u64 v[12:13], v[4:5], 0, v[140:141]
	v_lshlrev_b32_e32 v4, 2, v173
	v_lshl_add_u64 v[0:1], v[0:1], 0, v[128:129]
	v_lshlrev_b64 v[2:3], 12, v[2:3]
	v_or_b32_e32 v128, s38, v158
	s_mov_b32 s98, s40
	s_mov_b32 s99, s39
	v_lshlrev_b32_e32 v222, 6, v173
	v_lshl_add_u64 v[216:217], v[148:149], 0, s[98:99]
	v_or_b32_e32 v222, v222, v130
	v_or_b32_e32 v218, v216, v132
	v_mov_b32_e32 v219, v217
	v_lshlrev_b64 v[220:221], 11, v[218:219]
	v_lshlrev_b32_e32 v222, 1, v222
	v_or_b32_e32 v220, v220, v222
	v_lshl_add_u64 v[218:219], s[36:37], 0, v[220:221]
	v_mov_b32_e32 v230, 0x4000
	v_mov_b32_e32 v231, 0
	global_load_dwordx4 v[200:203], v[218:219], off
	v_lshl_add_u64 v[218:219], v[218:219], 0, v[230:231]
	global_load_dwordx4 v[204:207], v[218:219], off
	v_lshl_add_u64 v[218:219], v[218:219], 0, v[230:231]
	global_load_dwordx4 v[208:211], v[218:219], off
	v_lshl_add_u64 v[218:219], v[218:219], 0, v[230:231]
	global_load_dwordx4 v[212:215], v[218:219], off
	global_load_dwordx4 v[64:67], v[12:13], off
	global_load_dwordx4 v[68:71], v[12:13], off offset:32
	global_load_dword v10, v4, s[14:15]
	v_lshl_add_u64 v[4:5], s[34:35], 0, v[2:3]
	v_lshlrev_b64 v[2:3], 9, v[128:129]
	v_or_b32_e32 v128, s38, v159
	v_lshl_add_u64 v[2:3], v[0:1], 0, v[2:3]
	v_lshlrev_b64 v[6:7], 9, v[128:129]
	v_lshl_add_u64 v[2:3], v[2:3], 0, v[142:143]
	v_lshl_add_u64 v[6:7], v[0:1], 0, v[6:7]
	v_lshl_add_u64 v[6:7], v[6:7], 0, v[142:143]
	global_load_dwordx4 v[80:83], v[2:3], off
	global_load_dwordx4 v[84:87], v[6:7], off
	v_lshl_add_u64 v[2:3], v[4:5], 0, v[144:145]
	s_lshl_b64 s[0:1], s[38:39], 1
	v_lshl_add_u64 v[6:7], v[2:3], 0, s[0:1]
	v_lshl_add_u64 v[6:7], v[6:7], 0, v[142:143]
	v_lshl_add_u64 v[4:5], v[4:5], 0, v[146:147]
	global_load_dwordx4 v[88:91], v[6:7], off
	v_lshl_add_u64 v[8:9], v[4:5], 0, s[0:1]
	v_lshl_add_u64 v[8:9], v[8:9], 0, v[142:143]
	global_load_dwordx4 v[92:95], v[8:9], off
	global_load_dwordx4 v[72:75], v[12:13], off offset:64
	global_load_dwordx4 v[76:79], v[12:13], off offset:96
	s_lshr_b32 s41, s41, 1
	s_lshr_b32 s46, s46, 6
	s_cmp_ge_u32 s46, s41
	s_barrier
	s_waitcnt vmcnt(3)
	ds_write_b128 v160, v[88:91] offset:9216
	ds_write_b128 v160, v[80:83]
	ds_write_b128 v160, v[84:87] offset:4608
	s_waitcnt vmcnt(2)
	ds_write_b128 v160, v[92:95] offset:13824
	s_waitcnt vmcnt(0)
	s_cbranch_scc1 .LBB0_344
	s_add_i32 s0, s38, 64
	v_or_b32_e32 v128, s0, v158
	v_lshlrev_b64 v[12:13], 9, v[128:129]
	v_or_b32_e32 v128, s0, v159
	v_lshl_add_u64 v[12:13], v[0:1], 0, v[12:13]
	v_lshlrev_b64 v[14:15], 9, v[128:129]
	v_lshl_add_u64 v[12:13], v[12:13], 0, v[142:143]
	v_lshl_add_u64 v[14:15], v[0:1], 0, v[14:15]
	v_lshl_add_u64 v[14:15], v[14:15], 0, v[142:143]
	global_load_dwordx4 v[80:83], v[12:13], off
	global_load_dwordx4 v[84:87], v[14:15], off
	global_load_dwordx4 v[88:91], v[6:7], off offset:128
	global_load_dwordx4 v[92:95], v[8:9], off offset:128

; DI unsigned pack2(float a, float b) { f32x2_t v = {a, b}; bf16x2_t r = __builtin_convertvector(v, bf16x2_t); return __builtin_bit_cast(unsigned, r); }
; DI float bflo(unsigned u) { return __uint_as_float(u << 16); }
; DI float bfhi(unsigned u) { return __uint_as_float(u & 0xffff0000u); }
; DI float siluf_(float x) { return x * __builtin_amdgcn_rcpf(1.f + __expf(-x)); }
; DI void attn_write_staged(const f32x16& o0, const f32x16& o1, bf16_t* og, const bf16_t* z, size_t tok0, int head, int lane, bf16_t* wl) {
;   const int q = lane & 31, h = lane >> 5;
; #pragma unroll
;   for (int dt = 0; dt < 2; ++dt)
; #pragma unroll
;     for (int q4 = 0; q4 < 4; ++q4) {
;       const f32x16& o = dt ? o1 : o0;
;       *(uint2*)(wl + q * 72 + dt * 32 + 8 * q4 + 4 * h) = make_uint2(pack2(o[4 * q4], o[4 * q4 + 1]), pack2(o[4 * q4 + 2], o[4 * q4 + 3]));
;     }
; #pragma unroll
;   for (int k = 0; k < 4; ++k) {
;     const int ci = lane + 64 * k, row = ci >> 3, c8 = ci & 7;
;     const u32x4 ov = *(const u32x4*)(wl + row * 72 + c8 * 8);
;     const size_t off = (tok0 + row) * 1024 + head * 64 + c8 * 8;
;     const u32x4 zv = ldg16(z + off);
;     u32x4 r;
;     r.x = pack2(bflo(ov.x) * siluf_(bflo(zv.x)), bfhi(ov.x) * siluf_(bfhi(zv.x)));
;     r.y = pack2(bflo(ov.y) * siluf_(bflo(zv.y)), bfhi(ov.y) * siluf_(bfhi(zv.y)));
;     r.z = pack2(bflo(ov.z) * siluf_(bflo(zv.z)), bfhi(ov.z) * siluf_(bfhi(zv.z)));
;     r.w = pack2(bflo(ov.w) * siluf_(bflo(zv.w)), bfhi(ov.w) * siluf_(bfhi(zv.w)));
;     *(u32x4*)(og + off) = r;
;   }
; DI void phase_attn_mla(const Params& P, bf16_t* og, unsigned char* smem, int L, int G) {
;     ...
;     const float il = 1.f / l;
; #pragma unroll
;     for (int q = 0; q < 16; ++q) { o0[q] *= il; o1[q] *= il; }
;     attn_write_staged(o0, o1, og, big + ML_Z, (size_t)b * SEQ + t0, head, lane, (bf16_t*)(smem + 49152) + w * (32 * 72));
.LBB0_771:
	v_ashrrev_i32_e32 v163, 31, v162
	v_lshl_add_u64 v[2:3], s[20:21], 0, v[162:163]
	v_or_b32_e32 v0, s18, v138
	v_or_b32_e32 v4, v2, v146
	v_mov_b32_e32 v5, v3
	v_lshlrev_b64 v[48:49], 11, v[4:5]
	v_lshlrev_b32_e32 v50, 1, v0
	v_or_b32_e32 v48, v48, v50
	v_lshl_add_u64 v[4:5], s[10:11], 0, v[48:49]
	v_div_scale_f32 v0, s[18:19], v165, v165, 1.0
	v_rcp_f32_e32 v8, v0
	v_div_scale_f32 v9, vcc, 1.0, v165, 1.0
	v_add_u32_e32 v51, 0xc000, v177
	v_fma_f32 v10, -v0, v8, 1.0
	v_fmac_f32_e32 v8, v10, v8
	v_mul_f32_e32 v10, v9, v8
	v_fma_f32 v11, -v0, v10, v9
	v_fmac_f32_e32 v10, v11, v8
	v_fma_f32 v0, -v0, v10, v9
	v_div_fmas_f32 v0, v0, v8, v10
	v_div_fixup_f32 v0, v0, v165, 1.0
	v_pk_mul_f32 v[8:9], v[32:33], v[0:1] op_sel_hi:[1,0]
	v_pk_mul_f32 v[10:11], v[16:17], v[0:1] op_sel_hi:[1,0]
	v_pk_mul_f32 v[12:13], v[34:35], v[0:1] op_sel_hi:[1,0]
	v_pk_mul_f32 v[14:15], v[18:19], v[0:1] op_sel_hi:[1,0]
	v_pk_mul_f32 v[16:17], v[36:37], v[0:1] op_sel_hi:[1,0]
	v_pk_mul_f32 v[18:19], v[20:21], v[0:1] op_sel_hi:[1,0]
	v_pk_mul_f32 v[20:21], v[38:39], v[0:1] op_sel_hi:[1,0]
	v_pk_mul_f32 v[24:25], v[24:25], v[0:1] op_sel_hi:[1,0]
	v_pk_mul_f32 v[26:27], v[26:27], v[0:1] op_sel_hi:[1,0]
	v_pk_mul_f32 v[22:23], v[22:23], v[0:1] op_sel_hi:[1,0]
	v_pk_mul_f32 v[32:33], v[40:41], v[0:1] op_sel_hi:[1,0]
	v_pk_mul_f32 v[34:35], v[42:43], v[0:1] op_sel_hi:[1,0]
	v_pk_mul_f32 v[36:37], v[44:45], v[0:1] op_sel_hi:[1,0]
	v_pk_mul_f32 v[28:29], v[28:29], v[0:1] op_sel_hi:[1,0]
	v_pk_mul_f32 v[38:39], v[46:47], v[0:1] op_sel_hi:[1,0]
	v_pk_mul_f32 v[30:31], v[30:31], v[0:1] op_sel_hi:[1,0]
	v_cvt_pk_bf16_f32 v8, v8, v9
	v_cvt_pk_bf16_f32 v9, v12, v13
	v_cvt_pk_bf16_f32 v12, v16, v17
	v_cvt_pk_bf16_f32 v13, v20, v21
	v_cvt_pk_bf16_f32 v10, v10, v11
	v_cvt_pk_bf16_f32 v11, v14, v15
	v_cvt_pk_bf16_f32 v14, v18, v19
	v_cvt_pk_bf16_f32 v18, v24, v25
	v_cvt_pk_bf16_f32 v19, v26, v27
	v_cvt_pk_bf16_f32 v16, v32, v33
	v_cvt_pk_bf16_f32 v17, v34, v35
	v_cvt_pk_bf16_f32 v20, v36, v37
	v_cvt_pk_bf16_f32 v21, v38, v39
	v_cvt_pk_bf16_f32 v15, v22, v23
	v_cvt_pk_bf16_f32 v22, v28, v29
	v_cvt_pk_bf16_f32 v23, v30, v31
	ds_write2_b64 v51, v[8:9], v[12:13] offset1:2
	ds_write2_b64 v51, v[16:17], v[20:21] offset0:4 offset1:6
	ds_write2_b64 v51, v[10:11], v[14:15] offset0:8 offset1:10
	ds_write2_b64 v51, v[18:19], v[22:23] offset0:12 offset1:14
	ds_read_b128 v[8:11], v181 offset:49152
	ds_read_b128 v[12:15], v181 offset:50304
	s_add_i32 s38, s38, s74
	s_cmpk_gt_i32 s38, 0xfff
	s_waitcnt lgkmcnt(1)
	v_lshlrev_b32_e32 v16, 16, v8
	v_and_b32_e32 v17, 0xffff0000, v8
	v_lshlrev_b32_e32 v8, 16, v9
	v_and_b32_e32 v9, 0xffff0000, v9
	s_waitcnt vmcnt(0)
	v_mov_b32_e32 v4, v204
	v_mov_b32_e32 v5, v205
	v_mov_b32_e32 v6, v206
	v_mov_b32_e32 v7, v207
	v_lshlrev_b32_e32 v18, 16, v4
	v_and_b32_e32 v19, 0xffff0000, v4
	v_lshlrev_b32_e32 v4, 16, v5
	v_and_b32_e32 v5, 0xffff0000, v5
	v_lshlrev_b32_e32 v20, 16, v6
	v_and_b32_e32 v21, 0xffff0000, v6
	v_mul_f32_e32 v0, 0xbfb8aa3b, v18
	v_mul_f32_e32 v6, 0xbfb8aa3b, v19
	v_mul_f32_e32 v22, 0xbfb8aa3b, v4
	v_mul_f32_e32 v23, 0xbfb8aa3b, v5
	v_exp_f32_e32 v0, v0
	v_exp_f32_e32 v6, v6
	v_exp_f32_e32 v22, v22
	v_exp_f32_e32 v23, v23
	v_mul_f32_e32 v24, 0xbfb8aa3b, v20
	v_mul_f32_e32 v25, 0xbfb8aa3b, v21
	v_add_f32_e32 v0, 1.0, v0
	v_add_f32_e32 v6, 1.0, v6
	v_exp_f32_e32 v26, v24
	v_exp_f32_e32 v27, v25
	v_add_f32_e32 v24, 1.0, v22
	v_add_f32_e32 v25, 1.0, v23
	v_rcp_f32_e32 v22, v0
	v_rcp_f32_e32 v23, v6
	v_rcp_f32_e32 v24, v24
	v_rcp_f32_e32 v25, v25
	v_add_f32_e32 v0, 1.0, v26
	v_pk_mul_f32 v[18:19], v[22:23], v[18:19]
	v_rcp_f32_e32 v26, v0
	v_pk_mul_f32 v[16:17], v[18:19], v[16:17]
	v_add_f32_e32 v0, 1.0, v27
	v_lshlrev_b32_e32 v18, 16, v7
	v_pk_mul_f32 v[4:5], v[24:25], v[4:5]
	v_rcp_f32_e32 v27, v0
	v_and_b32_e32 v19, 0xffff0000, v7
	v_mul_f32_e32 v0, 0xbfb8aa3b, v18
	v_pk_mul_f32 v[8:9], v[4:5], v[8:9]
	v_exp_f32_e32 v0, v0
	v_mul_f32_e32 v6, 0xbfb8aa3b, v19
	v_cvt_pk_bf16_f32 v5, v8, v9
	v_lshlrev_b32_e32 v8, 16, v10
	v_and_b32_e32 v9, 0xffff0000, v10
	v_exp_f32_e32 v10, v6
	v_cvt_pk_bf16_f32 v4, v16, v17
	v_pk_mul_f32 v[16:17], v[26:27], v[20:21]
	v_add_f32_e32 v0, 1.0, v0
	v_pk_mul_f32 v[6:7], v[16:17], v[8:9]
	v_rcp_f32_e32 v8, v0
	v_add_f32_e32 v0, 1.0, v10
	v_rcp_f32_e32 v9, v0
	v_lshlrev_b32_e32 v10, 16, v11
	v_and_b32_e32 v11, 0xffff0000, v11
	v_cvt_pk_bf16_f32 v6, v6, v7
	v_pk_mul_f32 v[8:9], v[8:9], v[18:19]
	s_waitcnt lgkmcnt(0)
; DI unsigned pack2(float a, float b) { f32x2_t v = {a, b}; bf16x2_t r = __builtin_convertvector(v, bf16x2_t); return __builtin_bit_cast(unsigned, r); }
; DI float bflo(unsigned u) { return __uint_as_float(u << 16); }
; DI float bfhi(unsigned u) { return __uint_as_float(u & 0xffff0000u); }
; DI float siluf_(float x) { return x * __builtin_amdgcn_rcpf(1.f + __expf(-x)); }
; DI void attn_write_staged(const f32x16& o0, const f32x16& o1, bf16_t* og, const bf16_t* z, size_t tok0, int head, int lane, bf16_t* wl) {
;     ...
; #pragma unroll
;   for (int k = 0; k < 4; ++k) {
;     const int ci = lane + 64 * k, row = ci >> 3, c8 = ci & 7;
;     const u32x4 ov = *(const u32x4*)(wl + row * 72 + c8 * 8);
;     const size_t off = (tok0 + row) * 1024 + head * 64 + c8 * 8;
;     const u32x4 zv = ldg16(z + off);
;     u32x4 r;
;     r.x = pack2(bflo(ov.x) * siluf_(bflo(zv.x)), bfhi(ov.x) * siluf_(bfhi(zv.x)));
;     r.y = pack2(bflo(ov.y) * siluf_(bflo(zv.y)), bfhi(ov.y) * siluf_(bfhi(zv.y)));
;     r.z = pack2(bflo(ov.z) * siluf_(bflo(zv.z)), bfhi(ov.z) * siluf_(bfhi(zv.z)));
;     r.w = pack2(bflo(ov.w) * siluf_(bflo(zv.w)), bfhi(ov.w) * siluf_(bfhi(zv.w)));
;     *(u32x4*)(og + off) = r;
;   }
	v_lshlrev_b32_e32 v18, 16, v14
	v_pk_mul_f32 v[8:9], v[8:9], v[10:11]
	v_or_b32_e32 v10, v2, v150
	v_cvt_pk_bf16_f32 v7, v8, v9
	v_lshl_add_u64 v[8:9], s[94:95], 0, v[48:49]
	global_store_dwordx4 v[8:9], v[4:7], off
	v_mov_b32_e32 v11, v3
	v_lshlrev_b64 v[16:17], 11, v[10:11]
	v_or_b32_e32 v4, v2, v148
	v_mov_b32_e32 v5, v3
	v_lshlrev_b64 v[8:9], 11, v[4:5]
	v_or_b32_e32 v8, v8, v50
	v_lshl_add_u64 v[4:5], s[10:11], 0, v[8:9]
	v_lshlrev_b32_e32 v10, 16, v12
	v_and_b32_e32 v11, 0xffff0000, v12
	v_lshlrev_b32_e32 v12, 16, v13
	v_and_b32_e32 v13, 0xffff0000, v13
	v_and_b32_e32 v19, 0xffff0000, v14
	v_lshlrev_b32_e32 v14, 16, v15
	v_and_b32_e32 v15, 0xffff0000, v15
	v_lshl_add_u64 v[8:9], s[94:95], 0, v[8:9]
	v_or_b32_e32 v16, v16, v50
	v_or_b32_e32 v2, v2, v152
	v_mov_b32_e32 v4, v208
	v_mov_b32_e32 v5, v209
	v_mov_b32_e32 v6, v210
	v_mov_b32_e32 v7, v211
	v_lshlrev_b32_e32 v20, 16, v4
	v_and_b32_e32 v21, 0xffff0000, v4
	v_lshlrev_b32_e32 v4, 16, v5
	v_and_b32_e32 v5, 0xffff0000, v5
	v_lshlrev_b32_e32 v22, 16, v6
	v_and_b32_e32 v23, 0xffff0000, v6
	v_lshlrev_b32_e32 v6, 16, v7
	v_and_b32_e32 v7, 0xffff0000, v7
	v_mul_f32_e32 v0, 0xbfb8aa3b, v20
	v_mul_f32_e32 v24, 0xbfb8aa3b, v21
	v_mul_f32_e32 v25, 0xbfb8aa3b, v4
	v_mul_f32_e32 v26, 0xbfb8aa3b, v5
	v_mul_f32_e32 v27, 0xbfb8aa3b, v22
	v_mul_f32_e32 v28, 0xbfb8aa3b, v23
	v_mul_f32_e32 v29, 0xbfb8aa3b, v6
	v_mul_f32_e32 v30, 0xbfb8aa3b, v7
	v_exp_f32_e32 v0, v0
	v_exp_f32_e32 v24, v24
	v_exp_f32_e32 v25, v25
	v_exp_f32_e32 v26, v26
	v_exp_f32_e32 v27, v27
	v_exp_f32_e32 v28, v28
	v_exp_f32_e32 v29, v29
	v_exp_f32_e32 v30, v30
	v_add_f32_e32 v0, 1.0, v0
	v_add_f32_e32 v31, 1.0, v24
	v_add_f32_e32 v32, 1.0, v25
	v_add_f32_e32 v33, 1.0, v26
	v_add_f32_e32 v34, 1.0, v27
	v_add_f32_e32 v35, 1.0, v28
	v_add_f32_e32 v36, 1.0, v29
	v_add_f32_e32 v37, 1.0, v30
	v_rcp_f32_e32 v24, v0
	v_rcp_f32_e32 v25, v31
	v_rcp_f32_e32 v26, v32
	v_rcp_f32_e32 v27, v33
	v_rcp_f32_e32 v28, v34
	v_rcp_f32_e32 v29, v35
	v_rcp_f32_e32 v30, v36
	v_rcp_f32_e32 v31, v37
	v_pk_mul_f32 v[20:21], v[24:25], v[20:21]
	v_pk_mul_f32 v[4:5], v[26:27], v[4:5]
	v_pk_mul_f32 v[22:23], v[28:29], v[22:23]
	v_pk_mul_f32 v[6:7], v[30:31], v[6:7]
	v_pk_mul_f32 v[10:11], v[20:21], v[10:11]
	v_pk_mul_f32 v[12:13], v[4:5], v[12:13]
	v_pk_mul_f32 v[18:19], v[22:23], v[18:19]
	v_pk_mul_f32 v[14:15], v[6:7], v[14:15]
	v_cvt_pk_bf16_f32 v4, v10, v11
	v_cvt_pk_bf16_f32 v5, v12, v13
	v_cvt_pk_bf16_f32 v6, v18, v19
	v_cvt_pk_bf16_f32 v7, v14, v15
	global_store_dwordx4 v[8:9], v[4:7], off
	ds_read_b128 v[8:11], v181 offset:51456
	ds_read_b128 v[12:15], v181 offset:52608
	v_lshl_add_u64 v[4:5], s[10:11], 0, v[16:17]
	v_lshlrev_b64 v[18:19], 11, v[2:3]
	s_waitcnt lgkmcnt(1)
	v_lshlrev_b32_e32 v2, 16, v8
	v_and_b32_e32 v3, 0xffff0000, v8
	v_lshlrev_b32_e32 v8, 16, v9
	v_and_b32_e32 v9, 0xffff0000, v9
	v_lshlrev_b32_e32 v22, 16, v10
	v_and_b32_e32 v23, 0xffff0000, v10
	v_lshlrev_b32_e32 v10, 16, v11
	v_and_b32_e32 v11, 0xffff0000, v11
	v_or_b32_e32 v18, v18, v50
	v_lshl_add_u64 v[16:17], s[94:95], 0, v[16:17]
	v_lshl_add_u64 v[20:21], s[10:11], 0, v[18:19]
	v_mov_b32_e32 v4, v212
	v_mov_b32_e32 v5, v213
	v_mov_b32_e32 v6, v214
	v_mov_b32_e32 v7, v215
	v_lshlrev_b32_e32 v24, 16, v4
	v_and_b32_e32 v25, 0xffff0000, v4
	v_lshlrev_b32_e32 v4, 16, v5
	v_and_b32_e32 v5, 0xffff0000, v5
	v_lshlrev_b32_e32 v26, 16, v6
	v_and_b32_e32 v27, 0xffff0000, v6
	v_lshlrev_b32_e32 v6, 16, v7
	v_and_b32_e32 v7, 0xffff0000, v7
	v_mul_f32_e32 v0, 0xbfb8aa3b, v24
	v_mul_f32_e32 v28, 0xbfb8aa3b, v25
	v_mul_f32_e32 v29, 0xbfb8aa3b, v4
	v_mul_f32_e32 v30, 0xbfb8aa3b, v5
	v_mul_f32_e32 v31, 0xbfb8aa3b, v26
	v_mul_f32_e32 v32, 0xbfb8aa3b, v27
	v_mul_f32_e32 v33, 0xbfb8aa3b, v6
	v_mul_f32_e32 v34, 0xbfb8aa3b, v7
	v_exp_f32_e32 v0, v0
	v_exp_f32_e32 v28, v28
	v_exp_f32_e32 v29, v29
	v_exp_f32_e32 v30, v30
	v_exp_f32_e32 v31, v31
	v_exp_f32_e32 v32, v32
	v_exp_f32_e32 v33, v33
	v_exp_f32_e32 v34, v34
	v_add_f32_e32 v0, 1.0, v0
	v_add_f32_e32 v35, 1.0, v28
	v_add_f32_e32 v36, 1.0, v29
	v_add_f32_e32 v37, 1.0, v30
	v_add_f32_e32 v38, 1.0, v31
	v_add_f32_e32 v39, 1.0, v32
	v_add_f32_e32 v40, 1.0, v33
	v_add_f32_e32 v41, 1.0, v34
	v_rcp_f32_e32 v28, v0
	v_rcp_f32_e32 v29, v35
	v_rcp_f32_e32 v30, v36
	v_rcp_f32_e32 v31, v37
	v_rcp_f32_e32 v32, v38
	v_rcp_f32_e32 v33, v39
	v_rcp_f32_e32 v34, v40
	v_rcp_f32_e32 v35, v41
	v_pk_mul_f32 v[24:25], v[28:29], v[24:25]
	v_pk_mul_f32 v[4:5], v[30:31], v[4:5]
	v_pk_mul_f32 v[26:27], v[32:33], v[26:27]
	v_pk_mul_f32 v[6:7], v[34:35], v[6:7]
	v_pk_mul_f32 v[2:3], v[24:25], v[2:3]
	v_pk_mul_f32 v[4:5], v[4:5], v[8:9]
	v_pk_mul_f32 v[8:9], v[26:27], v[22:23]
	v_pk_mul_f32 v[6:7], v[6:7], v[10:11]
	v_cvt_pk_bf16_f32 v2, v2, v3
	v_cvt_pk_bf16_f32 v3, v4, v5
	v_cvt_pk_bf16_f32 v4, v8, v9
	v_cvt_pk_bf16_f32 v5, v6, v7
	global_store_dwordx4 v[16:17], v[2:5], off
	v_lshl_add_u64 v[6:7], s[94:95], 0, v[18:19]
	s_waitcnt lgkmcnt(0)
	v_lshlrev_b32_e32 v8, 16, v12
	v_and_b32_e32 v9, 0xffff0000, v12
	v_lshlrev_b32_e32 v10, 16, v13
	v_and_b32_e32 v11, 0xffff0000, v13
	v_lshlrev_b32_e32 v12, 16, v14
	v_and_b32_e32 v13, 0xffff0000, v14
	v_lshlrev_b32_e32 v14, 16, v15
	v_and_b32_e32 v15, 0xffff0000, v15
	v_mov_b32_e32 v2, v216
	v_mov_b32_e32 v3, v217
	v_mov_b32_e32 v4, v218
	v_mov_b32_e32 v5, v219
	v_lshlrev_b32_e32 v16, 16, v2
	v_and_b32_e32 v17, 0xffff0000, v2
	v_lshlrev_b32_e32 v2, 16, v3
	v_and_b32_e32 v3, 0xffff0000, v3
	v_lshlrev_b32_e32 v18, 16, v4
	v_and_b32_e32 v19, 0xffff0000, v4
	v_lshlrev_b32_e32 v4, 16, v5
	v_and_b32_e32 v5, 0xffff0000, v5
	v_mul_f32_e32 v0, 0xbfb8aa3b, v16
	v_mul_f32_e32 v20, 0xbfb8aa3b, v17
	v_mul_f32_e32 v21, 0xbfb8aa3b, v2
	v_mul_f32_e32 v22, 0xbfb8aa3b, v3
	v_mul_f32_e32 v23, 0xbfb8aa3b, v18
	v_mul_f32_e32 v24, 0xbfb8aa3b, v19
	v_mul_f32_e32 v25, 0xbfb8aa3b, v4
	v_mul_f32_e32 v26, 0xbfb8aa3b, v5
	v_exp_f32_e32 v0, v0
	v_exp_f32_e32 v20, v20
	v_exp_f32_e32 v21, v21
	v_exp_f32_e32 v22, v22
	v_exp_f32_e32 v23, v23
	v_exp_f32_e32 v24, v24
	v_exp_f32_e32 v25, v25
	v_exp_f32_e32 v26, v26
	v_add_f32_e32 v0, 1.0, v0
	v_add_f32_e32 v27, 1.0, v20
	v_add_f32_e32 v28, 1.0, v21
	v_add_f32_e32 v29, 1.0, v22
	v_add_f32_e32 v30, 1.0, v23
	v_add_f32_e32 v31, 1.0, v24
	v_add_f32_e32 v32, 1.0, v25
	v_add_f32_e32 v33, 1.0, v26
	v_rcp_f32_e32 v20, v0
	v_rcp_f32_e32 v21, v27
	v_rcp_f32_e32 v22, v28
	v_rcp_f32_e32 v23, v29
	v_rcp_f32_e32 v24, v30
	v_rcp_f32_e32 v25, v31
	v_rcp_f32_e32 v26, v32
	v_rcp_f32_e32 v27, v33
	v_pk_mul_f32 v[16:17], v[20:21], v[16:17]
	v_pk_mul_f32 v[2:3], v[22:23], v[2:3]
	v_pk_mul_f32 v[18:19], v[24:25], v[18:19]
	v_pk_mul_f32 v[4:5], v[26:27], v[4:5]
	v_pk_mul_f32 v[8:9], v[16:17], v[8:9]
	v_pk_mul_f32 v[10:11], v[2:3], v[10:11]
	v_pk_mul_f32 v[12:13], v[18:19], v[12:13]
	v_pk_mul_f32 v[14:15], v[4:5], v[14:15]
	v_cvt_pk_bf16_f32 v2, v8, v9
	v_cvt_pk_bf16_f32 v3, v10, v11
	v_cvt_pk_bf16_f32 v4, v12, v13
	v_cvt_pk_bf16_f32 v5, v14, v15
	global_store_dwordx4 v[6:7], v[2:5], off
	s_cbranch_scc1 .LBB0_793

; DI void attn_write_staged(const f32x16& o0, const f32x16& o1, bf16_t* og, const bf16_t* z, size_t tok0, int head, int lane, bf16_t* wl) {
;     ...
;   for (int k = 0; k < 4; ++k) {
;     const int ci = lane + 64 * k, row = ci >> 3, c8 = ci & 7;
;     const u32x4 ov = *(const u32x4*)(wl + row * 72 + c8 * 8);
;     const size_t off = (tok0 + row) * 1024 + head * 64 + c8 * 8;
;     const u32x4 zv = ldg16(z + off);
; DI void phase_attn_mla(const Params& P, bf16_t* og, unsigned char* smem, int L, int G) {
;     ...
;     int qt, bh; mla_item8(it, L, G, qt, bh);
;     const int b = bh >> 4, head = bh & 15;
;     const int t0 = qt * 256 + w * 32, t = t0 + r;
;     const size_t tok = (size_t)b * SEQ + t;
;     bf16x8 qf[6];
; #pragma unroll
;     for (int ks = 0; ks < 4; ++ks) qf[ks] = *(const bf16x8*)(big + ML_QN + tok * 1024 + head * 64 + ks * 16 + 8 * h);
; #pragma unroll
;     for (int ks = 0; ks < 2; ++ks) qf[4 + ks] = *(const bf16x8*)(big + ML_QR + tok * 512 + head * 32 + ks * 16 + 8 * h);
;     f32x16 o0, o1, s[2]; o_zero(o0, o1);
;     float m = NEGF, l = 0.f;
;     const bf16_t* knb = big + ML_KN + (size_t)b * SEQ * 1024 + head * 64;
;     const bf16_t* krb = big + ML_KR + (size_t)b * SEQ * 32;
;     const bf16_t* vb = big + ML_VT + (size_t)((b * 16 + head) * 64) * SEQ;
;     const int jhi = (qt * 256 + 255) >> 6;
;     KVR8 R; kv96x8_fetch(R, knb, krb, vb, 0, tid);
;     __syncthreads();
;     kv96x8_store(R, sK, sVt, tid);
;     if (0 < jhi) kv96x8_fetch(R, knb, krb, vb, 64, tid);
.LBB0_776:
	s_ashr_i32 s24, s26, 4
	v_lshl_add_u32 v162, s39, 8, v147
	v_or_b32_e32 v164, v162, v139
	s_ashr_i32 s25, s24, 31
	s_lshl_b64 s[20:21], s[24:25], 11
	v_ashrrev_i32_e32 v165, 31, v164
	v_lshl_add_u64 v[2:3], s[20:21], 0, v[164:165]
	s_and_b32 s14, s26, 15
	v_lshlrev_b64 v[4:5], 11, v[2:3]
	v_lshlrev_b64 v[2:3], 10, v[2:3]
	s_lshl_b32 s18, s14, 6
	s_mov_b32 s19, s15
	s_lshl_b32 s14, s14, 7
	v_lshl_add_u64 v[2:3], s[4:5], 0, v[2:3]
	s_lshl_b64 s[22:23], s[24:25], 22
	v_lshl_add_u64 v[2:3], v[2:3], 0, s[18:19]
	s_add_u32 s19, s31, s22
	s_addc_u32 s23, s33, s23
	s_add_u32 s22, s19, s14
	v_lshl_add_u64 v[4:5], s[2:3], 0, v[4:5]
	s_addc_u32 s23, s23, 0
	s_lshl_b64 s[24:25], s[24:25], 17
	v_lshl_add_u64 v[4:5], v[4:5], 0, s[14:15]
	s_add_u32 s24, s34, s24
	v_lshl_add_u64 v[4:5], v[4:5], 0, v[156:157]
	v_lshl_add_u64 v[2:3], v[2:3], 0, v[156:157]
	s_addc_u32 s25, s35, s25
	s_lshl_b32 s26, s26, 6
	v_lshl_add_u64 v[6:7], s[22:23], 0, v[136:137]
	v_mov_b32_e32 v220, v162
	v_ashrrev_i32_e32 v221, 31, v220
	v_lshl_add_u64 v[222:223], s[20:21], 0, v[220:221]
	v_or_b32_e32 v228, s18, v138
	v_or_b32_e32 v224, v222, v146
	v_mov_b32_e32 v225, v223
	v_lshlrev_b64 v[226:227], 11, v[224:225]
	v_lshlrev_b32_e32 v229, 1, v228
	v_or_b32_e32 v226, v226, v229
	v_lshl_add_u64 v[224:225], s[10:11], 0, v[226:227]
	v_mov_b32_e32 v234, 0x4000
	v_mov_b32_e32 v235, 0
	global_load_dwordx4 v[204:207], v[224:225], off
	v_lshl_add_u64 v[224:225], v[224:225], 0, v[234:235]
	global_load_dwordx4 v[208:211], v[224:225], off
	v_lshl_add_u64 v[224:225], v[224:225], 0, v[234:235]
	global_load_dwordx4 v[212:215], v[224:225], off
	v_lshl_add_u64 v[224:225], v[224:225], 0, v[234:235]
	global_load_dwordx4 v[216:219], v[224:225], off
	global_load_dwordx4 v[80:83], v[4:5], off offset:32
	global_load_dwordx4 v[84:87], v[4:5], off offset:64
	global_load_dwordx4 v[88:91], v[4:5], off offset:96
	global_load_dwordx4 v[92:95], v[2:3], off
	s_ashr_i32 s27, s26, 31
	v_lshl_add_u64 v[6:7], v[6:7], 0, v[158:159]
	global_load_dwordx4 v[96:99], v[2:3], off offset:32
	global_load_dwordx4 v[12:15], v[6:7], off
	v_lshl_add_u64 v[2:3], s[24:25], 0, v[140:141]
	s_lshl_b64 s[26:27], s[26:27], 12
	v_lshl_add_u64 v[10:11], v[2:3], 0, v[160:161]
	global_load_dwordx4 v[6:9], v[10:11], off
	v_lshl_add_u64 v[166:167], v[154:155], 0, s[26:27]
	global_load_dwordx4 v[100:103], v[4:5], off
	s_nop 0
	global_load_dwordx4 v[2:5], v[166:167], off
	s_barrier
	s_waitcnt vmcnt(3)
	ds_write_b128 v149, v[12:15]
	s_and_saveexec_b64 s[26:27], s[12:13]
	s_cbranch_execz .LBB0_778
	s_waitcnt vmcnt(2)
	ds_write_b128 v153, v[6:9] offset:128

; DI unsigned pack2(float a, float b) { f32x2_t v = {a, b}; bf16x2_t r = __builtin_convertvector(v, bf16x2_t); return __builtin_bit_cast(unsigned, r); }
; DI float bflo(unsigned u) { return __uint_as_float(u << 16); }
; DI float bfhi(unsigned u) { return __uint_as_float(u & 0xffff0000u); }
; DI float siluf_(float x) { return x * __builtin_amdgcn_rcpf(1.f + __expf(-x)); }
; DI void attn_write_staged(const f32x16& o0, const f32x16& o1, bf16_t* og, const bf16_t* z, size_t tok0, int head, int lane, bf16_t* wl) {
;   const int q = lane & 31, h = lane >> 5;
; #pragma unroll
;   for (int dt = 0; dt < 2; ++dt)
; #pragma unroll
;     for (int q4 = 0; q4 < 4; ++q4) {
;       const f32x16& o = dt ? o1 : o0;
;       *(uint2*)(wl + q * 72 + dt * 32 + 8 * q4 + 4 * h) = make_uint2(pack2(o[4 * q4], o[4 * q4 + 1]), pack2(o[4 * q4 + 2], o[4 * q4 + 3]));
;     }
; #pragma unroll
;   for (int k = 0; k < 4; ++k) {
;     const int ci = lane + 64 * k, row = ci >> 3, c8 = ci & 7;
;     const u32x4 ov = *(const u32x4*)(wl + row * 72 + c8 * 8);
;     const size_t off = (tok0 + row) * 1024 + head * 64 + c8 * 8;
;     const u32x4 zv = ldg16(z + off);
;     u32x4 r;
;     r.x = pack2(bflo(ov.x) * siluf_(bflo(zv.x)), bfhi(ov.x) * siluf_(bfhi(zv.x)));
;     r.y = pack2(bflo(ov.y) * siluf_(bflo(zv.y)), bfhi(ov.y) * siluf_(bfhi(zv.y)));
;     r.z = pack2(bflo(ov.z) * siluf_(bflo(zv.z)), bfhi(ov.z) * siluf_(bfhi(zv.z)));
;     r.w = pack2(bflo(ov.w) * siluf_(bflo(zv.w)), bfhi(ov.w) * siluf_(bfhi(zv.w)));
;     *(u32x4*)(og + off) = r;
;   }
; DI void phase_attn_swa(const Params& P, const float* sinks, bf16_t* og, unsigned char* smem, int L, int G) {
;     ...
;     const float il = 1.f / l;
; #pragma unroll
;     for (int q = 0; q < 16; ++q) { o0[q] *= il; o1[q] *= il; }
;     attn_write_staged(o0, o1, og, big + SW_Z, (size_t)b * SEQ + t0, head, lane, (bf16_t*)(smem + 40960) + w * (32 * 72));
.LBB0_1659:
	s_mov_b32 s11, s9
	v_lshlrev_b32_e32 v35, 6, v173
	v_lshl_add_u64 v[32:33], v[148:149], 0, s[10:11]
	v_or_b32_e32 v35, v35, v130
	v_or_b32_e32 v36, v32, v132
	v_mov_b32_e32 v37, v33
	v_lshlrev_b64 v[40:41], 11, v[36:37]
	v_lshlrev_b32_e32 v35, 1, v35
	v_or_b32_e32 v40, v40, v35
	v_lshl_add_u64 v[36:37], s[6:7], 0, v[40:41]
	v_div_scale_f32 v42, s[0:1], v34, v34, 1.0
	v_rcp_f32_e32 v43, v42
	v_div_scale_f32 v44, vcc, 1.0, v34, 1.0
	v_add_u32_e32 v45, 0xa000, v166
	v_fma_f32 v46, -v42, v43, 1.0
	v_fmac_f32_e32 v43, v46, v43
	v_mul_f32_e32 v46, v44, v43
	v_fma_f32 v47, -v42, v46, v44
	v_fmac_f32_e32 v46, v47, v43
	v_fma_f32 v42, -v42, v46, v44
	v_div_fmas_f32 v42, v42, v43, v46
	v_div_fixup_f32 v34, v42, v34, 1.0
	v_pk_mul_f32 v[0:1], v[34:35], v[0:1] op_sel_hi:[0,1]
	v_pk_mul_f32 v[2:3], v[34:35], v[2:3] op_sel_hi:[0,1]
	v_pk_mul_f32 v[4:5], v[34:35], v[4:5] op_sel_hi:[0,1]
	v_pk_mul_f32 v[20:21], v[20:21], v[34:35] op_sel_hi:[1,0]
	v_pk_mul_f32 v[6:7], v[34:35], v[6:7] op_sel_hi:[0,1]
	v_pk_mul_f32 v[22:23], v[22:23], v[34:35] op_sel_hi:[1,0]
	v_pk_mul_f32 v[24:25], v[24:25], v[34:35] op_sel_hi:[1,0]
	v_pk_mul_f32 v[10:11], v[34:35], v[10:11] op_sel_hi:[0,1]
	v_pk_mul_f32 v[26:27], v[26:27], v[34:35] op_sel_hi:[1,0]
	v_pk_mul_f32 v[12:13], v[34:35], v[12:13] op_sel_hi:[0,1]
	v_pk_mul_f32 v[16:17], v[16:17], v[34:35] op_sel_hi:[1,0]
	v_pk_mul_f32 v[18:19], v[18:19], v[34:35] op_sel_hi:[1,0]
	v_pk_mul_f32 v[8:9], v[34:35], v[8:9] op_sel_hi:[0,1]
	v_pk_mul_f32 v[28:29], v[28:29], v[34:35] op_sel_hi:[1,0]
	v_pk_mul_f32 v[14:15], v[34:35], v[14:15] op_sel_hi:[0,1]
	v_pk_mul_f32 v[30:31], v[30:31], v[34:35] op_sel_hi:[1,0]
	v_cvt_pk_bf16_f32 v0, v0, v1
	v_cvt_pk_bf16_f32 v1, v2, v3
	v_cvt_pk_bf16_f32 v2, v4, v5
	v_cvt_pk_bf16_f32 v3, v6, v7
	v_cvt_pk_bf16_f32 v5, v10, v11
	v_cvt_pk_bf16_f32 v6, v12, v13
	v_cvt_pk_bf16_f32 v10, v20, v21
	v_cvt_pk_bf16_f32 v11, v22, v23
	v_cvt_pk_bf16_f32 v12, v24, v25
	v_cvt_pk_bf16_f32 v13, v26, v27
	v_cvt_pk_bf16_f32 v4, v8, v9
	v_cvt_pk_bf16_f32 v7, v14, v15
	v_cvt_pk_bf16_f32 v8, v16, v17
	v_cvt_pk_bf16_f32 v9, v18, v19
	v_cvt_pk_bf16_f32 v14, v28, v29
	v_cvt_pk_bf16_f32 v15, v30, v31
	ds_write2_b64 v45, v[0:1], v[2:3] offset1:2
	ds_write2_b64 v45, v[4:5], v[6:7] offset0:4 offset1:6
	ds_write2_b64 v45, v[8:9], v[10:11] offset0:8 offset1:10
	ds_write2_b64 v45, v[12:13], v[14:15] offset0:12 offset1:14
	ds_read_b128 v[0:3], v167 offset:40960
	ds_read_b128 v[4:7], v167 offset:42112
	s_add_i32 s16, s16, s74
	s_cmpk_gt_i32 s16, 0xfff
	s_waitcnt lgkmcnt(1)
	v_lshlrev_b32_e32 v8, 16, v0
	v_and_b32_e32 v9, 0xffff0000, v0
	v_lshlrev_b32_e32 v0, 16, v1
	v_and_b32_e32 v1, 0xffff0000, v1
	s_waitcnt vmcnt(0)
	v_mov_b32_e32 v36, v200
	v_mov_b32_e32 v37, v201
	v_mov_b32_e32 v38, v202
	v_mov_b32_e32 v39, v203
	v_lshlrev_b32_e32 v10, 16, v36
	v_and_b32_e32 v11, 0xffff0000, v36
	v_lshlrev_b32_e32 v12, 16, v37
	v_and_b32_e32 v13, 0xffff0000, v37
	v_mul_f32_e32 v16, 0xbfb8aa3b, v10
	v_mul_f32_e32 v17, 0xbfb8aa3b, v11
	v_mul_f32_e32 v18, 0xbfb8aa3b, v12
	v_mul_f32_e32 v19, 0xbfb8aa3b, v13
	v_exp_f32_e32 v16, v16
	v_exp_f32_e32 v17, v17
	v_exp_f32_e32 v18, v18
	v_exp_f32_e32 v19, v19
	v_lshlrev_b32_e32 v14, 16, v38
	v_and_b32_e32 v15, 0xffff0000, v38
	v_add_f32_e32 v16, 1.0, v16
	v_add_f32_e32 v17, 1.0, v17
	v_add_f32_e32 v18, 1.0, v18
	v_add_f32_e32 v19, 1.0, v19
	v_mul_f32_e32 v20, 0xbfb8aa3b, v14
	v_mul_f32_e32 v21, 0xbfb8aa3b, v15
	v_rcp_f32_e32 v16, v16
	v_rcp_f32_e32 v17, v17
	v_rcp_f32_e32 v18, v18
	v_rcp_f32_e32 v19, v19
	v_exp_f32_e32 v20, v20
	v_exp_f32_e32 v21, v21
	v_pk_mul_f32 v[10:11], v[16:17], v[10:11]
	v_pk_mul_f32 v[12:13], v[18:19], v[12:13]
	v_add_f32_e32 v20, 1.0, v20
	v_pk_mul_f32 v[8:9], v[10:11], v[8:9]
	v_pk_mul_f32 v[10:11], v[12:13], v[0:1]
	v_add_f32_e32 v1, 1.0, v21
	v_rcp_f32_e32 v20, v20
	v_rcp_f32_e32 v21, v1
	v_lshlrev_b32_e32 v12, 16, v39
	v_cvt_pk_bf16_f32 v0, v8, v9
	v_lshlrev_b32_e32 v8, 16, v2
	v_and_b32_e32 v9, 0xffff0000, v2
	v_and_b32_e32 v13, 0xffff0000, v39
	v_mul_f32_e32 v2, 0xbfb8aa3b, v12
	v_cvt_pk_bf16_f32 v1, v10, v11
	v_pk_mul_f32 v[10:11], v[20:21], v[14:15]
	v_exp_f32_e32 v2, v2
	v_mul_f32_e32 v14, 0xbfb8aa3b, v13
	v_exp_f32_e32 v14, v14
	v_pk_mul_f32 v[8:9], v[10:11], v[8:9]
	v_add_f32_e32 v2, 1.0, v2
	v_rcp_f32_e32 v10, v2
	v_add_f32_e32 v2, 1.0, v14
	v_rcp_f32_e32 v11, v2
	v_cvt_pk_bf16_f32 v2, v8, v9
	v_lshlrev_b32_e32 v8, 16, v3
	v_and_b32_e32 v9, 0xffff0000, v3
	v_pk_mul_f32 v[10:11], v[10:11], v[12:13]
	s_waitcnt lgkmcnt(0)
; DI unsigned pack2(float a, float b) { f32x2_t v = {a, b}; bf16x2_t r = __builtin_convertvector(v, bf16x2_t); return __builtin_bit_cast(unsigned, r); }
; DI float bflo(unsigned u) { return __uint_as_float(u << 16); }
; DI float bfhi(unsigned u) { return __uint_as_float(u & 0xffff0000u); }
; DI float siluf_(float x) { return x * __builtin_amdgcn_rcpf(1.f + __expf(-x)); }
; DI void attn_write_staged(const f32x16& o0, const f32x16& o1, bf16_t* og, const bf16_t* z, size_t tok0, int head, int lane, bf16_t* wl) {
;     ...
; #pragma unroll
;   for (int k = 0; k < 4; ++k) {
;     const int ci = lane + 64 * k, row = ci >> 3, c8 = ci & 7;
;     const u32x4 ov = *(const u32x4*)(wl + row * 72 + c8 * 8);
;     const size_t off = (tok0 + row) * 1024 + head * 64 + c8 * 8;
;     const u32x4 zv = ldg16(z + off);
;     u32x4 r;
;     r.x = pack2(bflo(ov.x) * siluf_(bflo(zv.x)), bfhi(ov.x) * siluf_(bfhi(zv.x)));
;     r.y = pack2(bflo(ov.y) * siluf_(bflo(zv.y)), bfhi(ov.y) * siluf_(bfhi(zv.y)));
;     r.z = pack2(bflo(ov.z) * siluf_(bflo(zv.z)), bfhi(ov.z) * siluf_(bfhi(zv.z)));
;     r.w = pack2(bflo(ov.w) * siluf_(bflo(zv.w)), bfhi(ov.w) * siluf_(bfhi(zv.w)));
;     *(u32x4*)(og + off) = r;
;   }
	v_lshlrev_b32_e32 v12, 16, v4
	v_pk_mul_f32 v[8:9], v[10:11], v[8:9]
	v_or_b32_e32 v10, v32, v136
	v_cvt_pk_bf16_f32 v3, v8, v9
	v_lshl_add_u64 v[8:9], s[94:95], 0, v[40:41]
	global_store_dwordx4 v[8:9], v[0:3], off
	v_mov_b32_e32 v11, v33
	v_and_b32_e32 v13, 0xffff0000, v4
	v_or_b32_e32 v0, v32, v134
	v_mov_b32_e32 v1, v33
	v_lshlrev_b64 v[8:9], 11, v[0:1]
	v_or_b32_e32 v8, v8, v35
	v_lshl_add_u64 v[0:1], s[6:7], 0, v[8:9]
	v_lshlrev_b32_e32 v4, 16, v5
	v_and_b32_e32 v5, 0xffff0000, v5
	v_lshlrev_b32_e32 v14, 16, v6
	v_and_b32_e32 v15, 0xffff0000, v6
	v_lshlrev_b32_e32 v6, 16, v7
	v_and_b32_e32 v7, 0xffff0000, v7
	v_lshlrev_b64 v[10:11], 11, v[10:11]
	v_lshl_add_u64 v[8:9], s[94:95], 0, v[8:9]
	v_or_b32_e32 v10, v10, v35
	v_or_b32_e32 v32, v32, v138
	v_mov_b32_e32 v0, v204
	v_mov_b32_e32 v1, v205
	v_mov_b32_e32 v2, v206
	v_mov_b32_e32 v3, v207
	v_lshlrev_b32_e32 v16, 16, v0
	v_and_b32_e32 v17, 0xffff0000, v0
	v_lshlrev_b32_e32 v0, 16, v1
	v_and_b32_e32 v1, 0xffff0000, v1
	v_lshlrev_b32_e32 v18, 16, v2
	v_and_b32_e32 v19, 0xffff0000, v2
	v_lshlrev_b32_e32 v2, 16, v3
	v_and_b32_e32 v3, 0xffff0000, v3
	v_mul_f32_e32 v20, 0xbfb8aa3b, v16
	v_mul_f32_e32 v21, 0xbfb8aa3b, v17
	v_mul_f32_e32 v22, 0xbfb8aa3b, v0
	v_mul_f32_e32 v23, 0xbfb8aa3b, v1
	v_mul_f32_e32 v24, 0xbfb8aa3b, v18
	v_mul_f32_e32 v25, 0xbfb8aa3b, v19
	v_mul_f32_e32 v26, 0xbfb8aa3b, v2
	v_mul_f32_e32 v27, 0xbfb8aa3b, v3
	v_exp_f32_e32 v20, v20
	v_exp_f32_e32 v21, v21
	v_exp_f32_e32 v22, v22
	v_exp_f32_e32 v23, v23
	v_exp_f32_e32 v24, v24
	v_exp_f32_e32 v25, v25
	v_exp_f32_e32 v26, v26
	v_exp_f32_e32 v27, v27
	v_add_f32_e32 v20, 1.0, v20
	v_add_f32_e32 v21, 1.0, v21
	v_add_f32_e32 v22, 1.0, v22
	v_add_f32_e32 v23, 1.0, v23
	v_add_f32_e32 v24, 1.0, v24
	v_add_f32_e32 v25, 1.0, v25
	v_add_f32_e32 v26, 1.0, v26
	v_add_f32_e32 v27, 1.0, v27
	v_rcp_f32_e32 v20, v20
	v_rcp_f32_e32 v21, v21
	v_rcp_f32_e32 v22, v22
	v_rcp_f32_e32 v23, v23
	v_rcp_f32_e32 v24, v24
	v_rcp_f32_e32 v25, v25
	v_rcp_f32_e32 v26, v26
	v_rcp_f32_e32 v27, v27
	v_pk_mul_f32 v[16:17], v[20:21], v[16:17]
	v_pk_mul_f32 v[0:1], v[22:23], v[0:1]
	v_pk_mul_f32 v[18:19], v[24:25], v[18:19]
	v_pk_mul_f32 v[2:3], v[26:27], v[2:3]
	v_pk_mul_f32 v[12:13], v[16:17], v[12:13]
	v_pk_mul_f32 v[4:5], v[0:1], v[4:5]
	v_pk_mul_f32 v[14:15], v[18:19], v[14:15]
	v_pk_mul_f32 v[6:7], v[2:3], v[6:7]
	v_cvt_pk_bf16_f32 v0, v12, v13
	v_cvt_pk_bf16_f32 v1, v4, v5
	v_cvt_pk_bf16_f32 v2, v14, v15
	v_cvt_pk_bf16_f32 v3, v6, v7
	global_store_dwordx4 v[8:9], v[0:3], off
	v_lshlrev_b64 v[12:13], 11, v[32:33]
	ds_read_b128 v[4:7], v167 offset:43264
	v_lshl_add_u64 v[0:1], s[6:7], 0, v[10:11]
	v_lshl_add_u64 v[14:15], s[94:95], 0, v[10:11]
	ds_read_b128 v[8:11], v167 offset:44416
	s_waitcnt lgkmcnt(1)
	v_lshlrev_b32_e32 v18, 16, v4
	v_and_b32_e32 v19, 0xffff0000, v4
	v_lshlrev_b32_e32 v4, 16, v5
	v_and_b32_e32 v5, 0xffff0000, v5
	v_lshlrev_b32_e32 v20, 16, v6
	v_and_b32_e32 v21, 0xffff0000, v6
	v_lshlrev_b32_e32 v6, 16, v7
	v_and_b32_e32 v7, 0xffff0000, v7
	v_or_b32_e32 v12, v12, v35
	v_lshl_add_u64 v[16:17], s[6:7], 0, v[12:13]
	v_mov_b32_e32 v0, v208
	v_mov_b32_e32 v1, v209
	v_mov_b32_e32 v2, v210
	v_mov_b32_e32 v3, v211
	v_lshlrev_b32_e32 v22, 16, v0
	v_and_b32_e32 v23, 0xffff0000, v0
	v_lshlrev_b32_e32 v0, 16, v1
	v_and_b32_e32 v1, 0xffff0000, v1
	v_lshlrev_b32_e32 v24, 16, v2
	v_and_b32_e32 v25, 0xffff0000, v2
	v_lshlrev_b32_e32 v2, 16, v3
	v_and_b32_e32 v3, 0xffff0000, v3
	v_mul_f32_e32 v26, 0xbfb8aa3b, v22
	v_mul_f32_e32 v27, 0xbfb8aa3b, v23
	v_mul_f32_e32 v28, 0xbfb8aa3b, v0
	v_mul_f32_e32 v29, 0xbfb8aa3b, v1
	v_mul_f32_e32 v30, 0xbfb8aa3b, v24
	v_mul_f32_e32 v31, 0xbfb8aa3b, v25
	v_mul_f32_e32 v32, 0xbfb8aa3b, v2
	v_mul_f32_e32 v33, 0xbfb8aa3b, v3
	v_exp_f32_e32 v26, v26
	v_exp_f32_e32 v27, v27
	v_exp_f32_e32 v28, v28
	v_exp_f32_e32 v29, v29
	v_exp_f32_e32 v30, v30
	v_exp_f32_e32 v31, v31
	v_exp_f32_e32 v32, v32
	v_exp_f32_e32 v33, v33
	v_add_f32_e32 v26, 1.0, v26
	v_add_f32_e32 v27, 1.0, v27
	v_add_f32_e32 v28, 1.0, v28
	v_add_f32_e32 v29, 1.0, v29
	v_add_f32_e32 v30, 1.0, v30
	v_add_f32_e32 v31, 1.0, v31
	v_add_f32_e32 v32, 1.0, v32
	v_add_f32_e32 v33, 1.0, v33
	v_rcp_f32_e32 v26, v26
	v_rcp_f32_e32 v27, v27
	v_rcp_f32_e32 v28, v28
	v_rcp_f32_e32 v29, v29
	v_rcp_f32_e32 v30, v30
	v_rcp_f32_e32 v31, v31
	v_rcp_f32_e32 v32, v32
	v_rcp_f32_e32 v33, v33
	v_pk_mul_f32 v[22:23], v[26:27], v[22:23]
	v_pk_mul_f32 v[0:1], v[28:29], v[0:1]
	v_pk_mul_f32 v[24:25], v[30:31], v[24:25]
	v_pk_mul_f32 v[2:3], v[32:33], v[2:3]
	v_pk_mul_f32 v[18:19], v[22:23], v[18:19]
	v_pk_mul_f32 v[4:5], v[0:1], v[4:5]
	v_pk_mul_f32 v[20:21], v[24:25], v[20:21]
	v_pk_mul_f32 v[6:7], v[2:3], v[6:7]
	v_cvt_pk_bf16_f32 v0, v18, v19
	v_cvt_pk_bf16_f32 v1, v4, v5
	v_cvt_pk_bf16_f32 v2, v20, v21
	v_cvt_pk_bf16_f32 v3, v6, v7
	global_store_dwordx4 v[14:15], v[0:3], off
	v_lshl_add_u64 v[4:5], s[94:95], 0, v[12:13]
	s_waitcnt lgkmcnt(0)
	v_lshlrev_b32_e32 v6, 16, v8
	v_and_b32_e32 v7, 0xffff0000, v8
	v_lshlrev_b32_e32 v8, 16, v9
	v_and_b32_e32 v9, 0xffff0000, v9
	v_lshlrev_b32_e32 v12, 16, v10
	v_and_b32_e32 v13, 0xffff0000, v10
	v_lshlrev_b32_e32 v10, 16, v11
	v_and_b32_e32 v11, 0xffff0000, v11
	v_mov_b32_e32 v0, v212
	v_mov_b32_e32 v1, v213
	v_mov_b32_e32 v2, v214
	v_mov_b32_e32 v3, v215
	v_lshlrev_b32_e32 v14, 16, v0
	v_and_b32_e32 v15, 0xffff0000, v0
	v_lshlrev_b32_e32 v0, 16, v1
	v_and_b32_e32 v1, 0xffff0000, v1
	v_lshlrev_b32_e32 v16, 16, v2
	v_and_b32_e32 v17, 0xffff0000, v2
	v_lshlrev_b32_e32 v2, 16, v3
	v_and_b32_e32 v3, 0xffff0000, v3
	v_mul_f32_e32 v18, 0xbfb8aa3b, v14
	v_mul_f32_e32 v19, 0xbfb8aa3b, v15
	v_mul_f32_e32 v20, 0xbfb8aa3b, v0
	v_mul_f32_e32 v21, 0xbfb8aa3b, v1
	v_mul_f32_e32 v22, 0xbfb8aa3b, v16
	v_mul_f32_e32 v23, 0xbfb8aa3b, v17
	v_mul_f32_e32 v24, 0xbfb8aa3b, v2
	v_mul_f32_e32 v25, 0xbfb8aa3b, v3
	v_exp_f32_e32 v18, v18
	v_exp_f32_e32 v19, v19
	v_exp_f32_e32 v20, v20
	v_exp_f32_e32 v21, v21
	v_exp_f32_e32 v22, v22
	v_exp_f32_e32 v23, v23
	v_exp_f32_e32 v24, v24
	v_exp_f32_e32 v25, v25
	v_add_f32_e32 v18, 1.0, v18
	v_add_f32_e32 v19, 1.0, v19
	v_add_f32_e32 v20, 1.0, v20
	v_add_f32_e32 v21, 1.0, v21
	v_add_f32_e32 v22, 1.0, v22
	v_add_f32_e32 v23, 1.0, v23
	v_add_f32_e32 v24, 1.0, v24
	v_add_f32_e32 v25, 1.0, v25
	v_rcp_f32_e32 v18, v18
	v_rcp_f32_e32 v19, v19
	v_rcp_f32_e32 v20, v20
	v_rcp_f32_e32 v21, v21
	v_rcp_f32_e32 v22, v22
	v_rcp_f32_e32 v23, v23
	v_rcp_f32_e32 v24, v24
	v_rcp_f32_e32 v25, v25
	v_pk_mul_f32 v[14:15], v[18:19], v[14:15]
	v_pk_mul_f32 v[0:1], v[20:21], v[0:1]
	v_pk_mul_f32 v[16:17], v[22:23], v[16:17]
	v_pk_mul_f32 v[2:3], v[24:25], v[2:3]
	v_pk_mul_f32 v[6:7], v[14:15], v[6:7]
	v_pk_mul_f32 v[8:9], v[0:1], v[8:9]
	v_pk_mul_f32 v[12:13], v[16:17], v[12:13]
	v_pk_mul_f32 v[10:11], v[2:3], v[10:11]
	v_cvt_pk_bf16_f32 v0, v6, v7
	v_cvt_pk_bf16_f32 v1, v8, v9
	v_cvt_pk_bf16_f32 v2, v12, v13
	v_cvt_pk_bf16_f32 v3, v10, v11
	global_store_dwordx4 v[4:5], v[0:3], off
	s_cbranch_scc1 .LBB0_1674

; DI void attn_write_staged(const f32x16& o0, const f32x16& o1, bf16_t* og, const bf16_t* z, size_t tok0, int head, int lane, bf16_t* wl) {
;     ...
;   for (int k = 0; k < 4; ++k) {
;     const int ci = lane + 64 * k, row = ci >> 3, c8 = ci & 7;
;     const u32x4 ov = *(const u32x4*)(wl + row * 72 + c8 * 8);
;     const size_t off = (tok0 + row) * 1024 + head * 64 + c8 * 8;
;     const u32x4 zv = ldg16(z + off);
; DI void phase_attn_swa(const Params& P, const float* sinks, bf16_t* og, unsigned char* smem, int L, int G) {
;     ...
;     int qt, bg; gqa_item(it, L, G, gi, qt, bg);
;     const int b = bg >> 2, g = bg & 3;
;     const int t0 = qt * 32, t = t0 + r, head = g * 4 + w;
;     const size_t tok = (size_t)b * SEQ + t;
;     bf16x8 qf[4];
; #pragma unroll
;     for (int ks = 0; ks < 4; ++ks) qf[ks] = *(const bf16x8*)(big + SW_Q + tok * 1024 + head * 64 + ks * 16 + 8 * h);
;     f32x16 o0, o1, s[2]; o_zero(o0, o1);
;     float m = sinks[head] * LOG2E, l = 1.f;
;     const bf16_t* kb = big + SW_K + (size_t)b * SEQ * 256 + g * 64;
;     const bf16_t* vb = big + SW_VT + (size_t)((b * 4 + g) * 64) * SEQ;
;     const int jlo = (t0 - 127 > 0 ? t0 - 127 : 0) >> 6, jhi = (t0 + 31) >> 6;
;     KVR R; kv64_fetch(R, kb, 256, vb, SEQ, jlo * 64, true, tid);
;     __syncthreads();
;     kv64_store(R, sK, sVt, tid);
;     if (jlo < jhi) kv64_fetch(R, kb, 256, vb, SEQ, jlo * 64 + 64, true, tid);
.LBB0_1664:
	v_ashrrev_i32_e32 v0, 2, v2
	s_lshl_b32 s10, s11, 5
	v_ashrrev_i32_e32 v1, 31, v0
	v_or_b32_e32 v150, s10, v135
	v_lshlrev_b64 v[148:149], 11, v[0:1]
	v_mov_b32_e32 v151, v129
	v_and_b32_e32 v3, 3, v2
	v_lshl_add_u64 v[4:5], v[148:149], 0, v[150:151]
	v_lshl_or_b32 v173, v3, 2, v133
	v_lshlrev_b64 v[4:5], 11, v[4:5]
	s_max_i32 s0, s10, 0x7f
	v_lshl_add_u64 v[4:5], s[76:77], 0, v[4:5]
	v_lshlrev_b32_e32 v128, 7, v173
	v_lshlrev_b64 v[0:1], 20, v[0:1]
	v_lshlrev_b32_e32 v2, 6, v2
	s_add_i32 s17, s0, 0xffffff81
	v_lshl_add_u64 v[4:5], v[4:5], 0, v[128:129]
	v_lshl_add_u64 v[0:1], s[66:67], 0, v[0:1]
	v_lshlrev_b32_e32 v128, 7, v3
	v_ashrrev_i32_e32 v3, 31, v2
	s_and_b32 s8, s17, 0xffffffc0
	v_lshl_add_u64 v[12:13], v[4:5], 0, v[140:141]
	v_lshlrev_b32_e32 v4, 2, v173
	v_lshl_add_u64 v[0:1], v[0:1], 0, v[128:129]
	v_lshlrev_b64 v[2:3], 12, v[2:3]
	v_or_b32_e32 v128, s8, v158
	s_mov_b32 s98, s10
	s_mov_b32 s99, s9
	v_lshlrev_b32_e32 v222, 6, v173
	v_lshl_add_u64 v[216:217], v[148:149], 0, s[98:99]
	v_or_b32_e32 v222, v222, v130
	v_or_b32_e32 v218, v216, v132
	v_mov_b32_e32 v219, v217
	v_lshlrev_b64 v[220:221], 11, v[218:219]
	v_lshlrev_b32_e32 v222, 1, v222
	v_or_b32_e32 v220, v220, v222
	v_lshl_add_u64 v[218:219], s[6:7], 0, v[220:221]
	v_mov_b32_e32 v230, 0x4000
	v_mov_b32_e32 v231, 0
	global_load_dwordx4 v[200:203], v[218:219], off
	v_lshl_add_u64 v[218:219], v[218:219], 0, v[230:231]
	global_load_dwordx4 v[204:207], v[218:219], off
	v_lshl_add_u64 v[218:219], v[218:219], 0, v[230:231]
	global_load_dwordx4 v[208:211], v[218:219], off
	v_lshl_add_u64 v[218:219], v[218:219], 0, v[230:231]
	global_load_dwordx4 v[212:215], v[218:219], off
	global_load_dwordx4 v[64:67], v[12:13], off
	global_load_dwordx4 v[68:71], v[12:13], off offset:32
	global_load_dword v10, v4, s[92:93]
	v_lshl_add_u64 v[4:5], s[4:5], 0, v[2:3]
	v_lshlrev_b64 v[2:3], 9, v[128:129]
	v_or_b32_e32 v128, s8, v159
	v_lshl_add_u64 v[2:3], v[0:1], 0, v[2:3]
	v_lshlrev_b64 v[6:7], 9, v[128:129]
	v_lshl_add_u64 v[2:3], v[2:3], 0, v[142:143]
	v_lshl_add_u64 v[6:7], v[0:1], 0, v[6:7]
	v_lshl_add_u64 v[6:7], v[6:7], 0, v[142:143]
	global_load_dwordx4 v[80:83], v[2:3], off
	global_load_dwordx4 v[84:87], v[6:7], off
	v_lshl_add_u64 v[2:3], v[4:5], 0, v[144:145]
	s_lshl_b64 s[0:1], s[8:9], 1
	v_lshl_add_u64 v[6:7], v[2:3], 0, s[0:1]
	v_lshl_add_u64 v[6:7], v[6:7], 0, v[142:143]
	v_lshl_add_u64 v[4:5], v[4:5], 0, v[146:147]
	global_load_dwordx4 v[88:91], v[6:7], off
	v_lshl_add_u64 v[8:9], v[4:5], 0, s[0:1]
	v_lshl_add_u64 v[8:9], v[8:9], 0, v[142:143]
	global_load_dwordx4 v[92:95], v[8:9], off
	global_load_dwordx4 v[72:75], v[12:13], off offset:64
	global_load_dwordx4 v[76:79], v[12:13], off offset:96
	s_lshr_b32 s11, s11, 1
	s_lshr_b32 s17, s17, 6
	s_cmp_ge_u32 s17, s11
	s_barrier
	s_waitcnt vmcnt(3)
	ds_write_b128 v160, v[88:91] offset:9216
	ds_write_b128 v160, v[80:83]
	ds_write_b128 v160, v[84:87] offset:4608
	s_waitcnt vmcnt(2)
	ds_write_b128 v160, v[92:95] offset:13824
	s_waitcnt vmcnt(0)
	s_cbranch_scc1 .LBB0_1666
	s_add_i32 s0, s8, 64
	v_or_b32_e32 v128, s0, v158
	v_lshlrev_b64 v[12:13], 9, v[128:129]
	v_or_b32_e32 v128, s0, v159
	v_lshl_add_u64 v[12:13], v[0:1], 0, v[12:13]
	v_lshlrev_b64 v[14:15], 9, v[128:129]
	v_lshl_add_u64 v[12:13], v[12:13], 0, v[142:143]
	v_lshl_add_u64 v[14:15], v[0:1], 0, v[14:15]
	v_lshl_add_u64 v[14:15], v[14:15], 0, v[142:143]
	global_load_dwordx4 v[80:83], v[12:13], off
	global_load_dwordx4 v[84:87], v[14:15], off
	global_load_dwordx4 v[88:91], v[6:7], off offset:128
	global_load_dwordx4 v[92:95], v[8:9], off offset:128
